# pooling queue item: hand-written fast path for tiles not at a sequence start - all 80 rows loaded up front, sliding-window means branch-free; sequence-start tiles keep the old path
# speedup vs baseline: 1.0077x; 1.0067x over previous
.LBB0_605:
	s_and_b64 vcc, exec, s[4:5]
	s_cbranch_vccz .LBB0_675
	s_add_i32 s2, s28, 0xfffffe80
	s_lshl_b32 s18, s2, 6
	s_mul_i32 s52, s2, 0x8c000
	s_and_b32 s19, s18, 0xfc0
	s_lshl_b64 s[4:5], s[52:53], 1
	v_mov_b32_e32 v0, v228
	s_add_u32 s4, s94, s4
	s_addc_u32 s5, s95, s5
	s_cmp_lg_u32 s19, 0
	s_cbranch_scc1 .Lpool_fast
	v_ashrrev_i32_e32 v1, 31, v0
	v_lshl_add_u64 v[2:3], v[0:1], 1, s[4:5]
	s_mov_b64 s[4:5], 0x2000
	s_movk_i32 s2, 0x7f
	v_lshl_add_u64 v[2:3], v[2:3], 0, s[4:5]
	v_cmp_lt_u32_e32 vcc, s2, v0
	s_and_saveexec_b64 s[4:5], vcc
	s_xor_b64 s[42:43], exec, s[4:5]
	s_cbranch_execz .LBB0_669
	v_ashrrev_i32_e32 v4, 7, v0
	s_cmp_lg_u32 s19, 0
	s_cselect_b64 s[8:9], -1, 0
	v_cmp_lt_i32_e32 vcc, 1, v4
	s_mov_b64 s[4:5], 0
	s_mov_b64 s[16:17], 0
	s_and_saveexec_b64 s[14:15], vcc
	s_xor_b64 s[14:15], exec, s[14:15]
	s_cbranch_execz .LBB0_626
	v_cmp_eq_u32_e32 vcc, 2, v4
	s_mov_b64 s[16:17], -1
	s_and_saveexec_b64 s[56:57], vcc
	s_cbranch_execz .LBB0_625
	v_cndmask_b32_e64 v1, 0, 1, s[8:9]
	v_mov_b32_e32 v16, 0
	v_cmp_ne_u32_e64 s[40:41], 1, v1
	s_andn2_b64 vcc, exec, s[8:9]
	v_mov_b32_e32 v20, 0
	s_cbranch_vccnz .LBB0_611
	v_add_co_u32_e32 v4, vcc, 0xfffe1600, v2
	s_nop 1
	v_addc_co_u32_e32 v5, vcc, -1, v3, vcc
	global_load_ushort v1, v[4:5], off
	s_waitcnt vmcnt(0) lgkmcnt(0)
	v_lshlrev_b32_e32 v20, 16, v1

.Lpool_fast:
	s_add_u32 s98, s4, 0xfffbc000
	s_addc_u32 s99, s5, -1
	v_lshlrev_b32_e32 v105, 1, v228
	global_load_ushort v20, v105, s[98:99]
	v_add_u32_e32 v106, 0x4600, v105
	global_load_ushort v21, v106, s[98:99]
	v_add_u32_e32 v106, 0x8c00, v105
	global_load_ushort v22, v106, s[98:99]
	v_add_u32_e32 v106, 0xd200, v105
	global_load_ushort v23, v106, s[98:99]
	v_add_u32_e32 v106, 0x11800, v105
	global_load_ushort v24, v106, s[98:99]
	v_add_u32_e32 v106, 0x15e00, v105
	global_load_ushort v25, v106, s[98:99]
	v_add_u32_e32 v106, 0x1a400, v105
	global_load_ushort v26, v106, s[98:99]
	v_add_u32_e32 v106, 0x1ea00, v105
	global_load_ushort v27, v106, s[98:99]
	v_add_u32_e32 v106, 0x23000, v105
	global_load_ushort v28, v106, s[98:99]
	v_add_u32_e32 v106, 0x27600, v105
	global_load_ushort v29, v106, s[98:99]
	v_add_u32_e32 v106, 0x2bc00, v105
	global_load_ushort v30, v106, s[98:99]
	v_add_u32_e32 v106, 0x30200, v105
	global_load_ushort v31, v106, s[98:99]
	v_add_u32_e32 v106, 0x34800, v105
	global_load_ushort v32, v106, s[98:99]
	v_add_u32_e32 v106, 0x38e00, v105
	global_load_ushort v33, v106, s[98:99]
	v_add_u32_e32 v106, 0x3d400, v105
	global_load_ushort v34, v106, s[98:99]
	v_add_u32_e32 v106, 0x41a00, v105
	global_load_ushort v35, v106, s[98:99]
	v_add_u32_e32 v106, 0x46000, v105
	global_load_ushort v36, v106, s[98:99]
	v_add_u32_e32 v106, 0x4a600, v105
	global_load_ushort v37, v106, s[98:99]
	v_add_u32_e32 v106, 0x4ec00, v105
	global_load_ushort v38, v106, s[98:99]
	v_add_u32_e32 v106, 0x53200, v105
	global_load_ushort v39, v106, s[98:99]
	v_add_u32_e32 v106, 0x57800, v105
	global_load_ushort v40, v106, s[98:99]
	v_add_u32_e32 v106, 0x5be00, v105
	global_load_ushort v41, v106, s[98:99]
	v_add_u32_e32 v106, 0x60400, v105
	global_load_ushort v42, v106, s[98:99]
	v_add_u32_e32 v106, 0x64a00, v105
	global_load_ushort v43, v106, s[98:99]
	v_add_u32_e32 v106, 0x69000, v105
	global_load_ushort v44, v106, s[98:99]
	v_add_u32_e32 v106, 0x6d600, v105
	global_load_ushort v45, v106, s[98:99]
	v_add_u32_e32 v106, 0x71c00, v105
	global_load_ushort v46, v106, s[98:99]
	v_add_u32_e32 v106, 0x76200, v105
	global_load_ushort v47, v106, s[98:99]
	v_add_u32_e32 v106, 0x7a800, v105
	global_load_ushort v48, v106, s[98:99]
	v_add_u32_e32 v106, 0x7ee00, v105
	global_load_ushort v49, v106, s[98:99]
	v_add_u32_e32 v106, 0x83400, v105
	global_load_ushort v50, v106, s[98:99]
	v_add_u32_e32 v106, 0x87a00, v105
	global_load_ushort v51, v106, s[98:99]
	v_add_u32_e32 v106, 0x8c000, v105
	global_load_ushort v52, v106, s[98:99]
	v_add_u32_e32 v106, 0x90600, v105
	global_load_ushort v53, v106, s[98:99]
	v_add_u32_e32 v106, 0x94c00, v105
	global_load_ushort v54, v106, s[98:99]
	v_add_u32_e32 v106, 0x99200, v105
	global_load_ushort v55, v106, s[98:99]
	v_add_u32_e32 v106, 0x9d800, v105
	global_load_ushort v56, v106, s[98:99]
	v_add_u32_e32 v106, 0xa1e00, v105
	global_load_ushort v57, v106, s[98:99]
	v_add_u32_e32 v106, 0xa6400, v105
	global_load_ushort v58, v106, s[98:99]
	v_add_u32_e32 v106, 0xaaa00, v105
	global_load_ushort v59, v106, s[98:99]
	v_add_u32_e32 v106, 0xaf000, v105
	global_load_ushort v60, v106, s[98:99]
	v_add_u32_e32 v106, 0xb3600, v105
	global_load_ushort v61, v106, s[98:99]
	v_add_u32_e32 v106, 0xb7c00, v105
	global_load_ushort v62, v106, s[98:99]
	v_add_u32_e32 v106, 0xbc200, v105
	global_load_ushort v63, v106, s[98:99]
	v_add_u32_e32 v106, 0xc0800, v105
	global_load_ushort v64, v106, s[98:99]
	v_add_u32_e32 v106, 0xc4e00, v105
	global_load_ushort v65, v106, s[98:99]
	v_add_u32_e32 v106, 0xc9400, v105
	global_load_ushort v66, v106, s[98:99]
	v_add_u32_e32 v106, 0xcda00, v105
	global_load_ushort v67, v106, s[98:99]
	v_add_u32_e32 v106, 0xd2000, v105
	global_load_ushort v68, v106, s[98:99]
	v_add_u32_e32 v106, 0xd6600, v105
	global_load_ushort v69, v106, s[98:99]
	v_add_u32_e32 v106, 0xdac00, v105
	global_load_ushort v70, v106, s[98:99]
	v_add_u32_e32 v106, 0xdf200, v105
	global_load_ushort v71, v106, s[98:99]
	v_add_u32_e32 v106, 0xe3800, v105
	global_load_ushort v72, v106, s[98:99]
	v_add_u32_e32 v106, 0xe7e00, v105
	global_load_ushort v73, v106, s[98:99]
	v_add_u32_e32 v106, 0xec400, v105
	global_load_ushort v74, v106, s[98:99]
	v_add_u32_e32 v106, 0xf0a00, v105
	global_load_ushort v75, v106, s[98:99]
	v_add_u32_e32 v106, 0xf5000, v105
	global_load_ushort v76, v106, s[98:99]
	v_add_u32_e32 v106, 0xf9600, v105
	global_load_ushort v77, v106, s[98:99]
	v_add_u32_e32 v106, 0xfdc00, v105
	global_load_ushort v79, v106, s[98:99]
	v_add_u32_e32 v106, 0x102200, v105
	global_load_ushort v80, v106, s[98:99]
	v_add_u32_e32 v106, 0x106800, v105
	global_load_ushort v81, v106, s[98:99]
	v_add_u32_e32 v106, 0x10ae00, v105
	global_load_ushort v82, v106, s[98:99]
	v_add_u32_e32 v106, 0x10f400, v105
	global_load_ushort v83, v106, s[98:99]
	v_add_u32_e32 v106, 0x113a00, v105
	global_load_ushort v84, v106, s[98:99]
	v_add_u32_e32 v106, 0x118000, v105
	global_load_ushort v85, v106, s[98:99]
	v_add_u32_e32 v106, 0x11c600, v105
	global_load_ushort v86, v106, s[98:99]
	v_add_u32_e32 v106, 0x120c00, v105
	global_load_ushort v87, v106, s[98:99]
	v_add_u32_e32 v106, 0x125200, v105
	global_load_ushort v88, v106, s[98:99]
	v_add_u32_e32 v106, 0x129800, v105
	global_load_ushort v89, v106, s[98:99]
	v_add_u32_e32 v106, 0x12de00, v105
	global_load_ushort v90, v106, s[98:99]
	v_add_u32_e32 v106, 0x132400, v105
	global_load_ushort v91, v106, s[98:99]
	v_add_u32_e32 v106, 0x136a00, v105
	global_load_ushort v92, v106, s[98:99]
	v_add_u32_e32 v106, 0x13b000, v105
	global_load_ushort v93, v106, s[98:99]
	v_add_u32_e32 v106, 0x13f600, v105
	global_load_ushort v94, v106, s[98:99]
	v_add_u32_e32 v106, 0x143c00, v105
	global_load_ushort v95, v106, s[98:99]
	v_add_u32_e32 v106, 0x148200, v105
	global_load_ushort v96, v106, s[98:99]
	v_add_u32_e32 v106, 0x14c800, v105
	global_load_ushort v97, v106, s[98:99]
	v_add_u32_e32 v106, 0x150e00, v105
	global_load_ushort v98, v106, s[98:99]
	v_add_u32_e32 v106, 0x155400, v105
	global_load_ushort v99, v106, s[98:99]
	v_add_u32_e32 v106, 0x159a00, v105
	global_load_ushort v100, v106, s[98:99]
	v_readfirstlane_b32 s2, v228
	s_lshr_b32 s2, s2, 7
	s_waitcnt vmcnt(0)
	v_lshlrev_b32_e32 v20, 16, v20
	v_lshlrev_b32_e32 v21, 16, v21
	v_lshlrev_b32_e32 v22, 16, v22
	v_lshlrev_b32_e32 v23, 16, v23
	v_lshlrev_b32_e32 v24, 16, v24
	v_lshlrev_b32_e32 v25, 16, v25
	v_lshlrev_b32_e32 v26, 16, v26
	v_lshlrev_b32_e32 v27, 16, v27
	v_lshlrev_b32_e32 v28, 16, v28
	v_lshlrev_b32_e32 v29, 16, v29
	v_lshlrev_b32_e32 v30, 16, v30
	v_lshlrev_b32_e32 v31, 16, v31
	v_lshlrev_b32_e32 v32, 16, v32
	v_lshlrev_b32_e32 v33, 16, v33
	v_lshlrev_b32_e32 v34, 16, v34
	v_lshlrev_b32_e32 v35, 16, v35
	v_lshlrev_b32_e32 v36, 16, v36
	v_lshlrev_b32_e32 v37, 16, v37
	v_lshlrev_b32_e32 v38, 16, v38
	v_lshlrev_b32_e32 v39, 16, v39
	v_lshlrev_b32_e32 v40, 16, v40
	v_lshlrev_b32_e32 v41, 16, v41
	v_lshlrev_b32_e32 v42, 16, v42
	v_lshlrev_b32_e32 v43, 16, v43
	v_lshlrev_b32_e32 v44, 16, v44
	v_lshlrev_b32_e32 v45, 16, v45
	v_lshlrev_b32_e32 v46, 16, v46
	v_lshlrev_b32_e32 v47, 16, v47
	v_lshlrev_b32_e32 v48, 16, v48
	v_lshlrev_b32_e32 v49, 16, v49
	v_lshlrev_b32_e32 v50, 16, v50
	v_lshlrev_b32_e32 v51, 16, v51
	v_lshlrev_b32_e32 v52, 16, v52
	v_lshlrev_b32_e32 v53, 16, v53
	v_lshlrev_b32_e32 v54, 16, v54
	v_lshlrev_b32_e32 v55, 16, v55
	v_lshlrev_b32_e32 v56, 16, v56
	v_lshlrev_b32_e32 v57, 16, v57
	v_lshlrev_b32_e32 v58, 16, v58
	v_lshlrev_b32_e32 v59, 16, v59
	v_lshlrev_b32_e32 v60, 16, v60
	v_lshlrev_b32_e32 v61, 16, v61
	v_lshlrev_b32_e32 v62, 16, v62
	v_lshlrev_b32_e32 v63, 16, v63
	v_lshlrev_b32_e32 v64, 16, v64
	v_lshlrev_b32_e32 v65, 16, v65
	v_lshlrev_b32_e32 v66, 16, v66
	v_lshlrev_b32_e32 v67, 16, v67
	v_lshlrev_b32_e32 v68, 16, v68
	v_lshlrev_b32_e32 v69, 16, v69
	v_lshlrev_b32_e32 v70, 16, v70
	v_lshlrev_b32_e32 v71, 16, v71
	v_lshlrev_b32_e32 v72, 16, v72
	v_lshlrev_b32_e32 v73, 16, v73
	v_lshlrev_b32_e32 v74, 16, v74
	v_lshlrev_b32_e32 v75, 16, v75
	v_lshlrev_b32_e32 v76, 16, v76
	v_lshlrev_b32_e32 v77, 16, v77
	v_lshlrev_b32_e32 v79, 16, v79
	v_lshlrev_b32_e32 v80, 16, v80
	v_lshlrev_b32_e32 v81, 16, v81
	v_lshlrev_b32_e32 v82, 16, v82
	v_lshlrev_b32_e32 v83, 16, v83
	v_lshlrev_b32_e32 v84, 16, v84
	v_lshlrev_b32_e32 v85, 16, v85
	v_lshlrev_b32_e32 v86, 16, v86
	v_lshlrev_b32_e32 v87, 16, v87
	v_lshlrev_b32_e32 v88, 16, v88
	v_lshlrev_b32_e32 v89, 16, v89
	v_lshlrev_b32_e32 v90, 16, v90
	v_lshlrev_b32_e32 v91, 16, v91
	v_lshlrev_b32_e32 v92, 16, v92
	v_lshlrev_b32_e32 v93, 16, v93
	v_lshlrev_b32_e32 v94, 16, v94
	v_lshlrev_b32_e32 v95, 16, v95
	v_lshlrev_b32_e32 v96, 16, v96
	v_lshlrev_b32_e32 v97, 16, v97
	v_lshlrev_b32_e32 v98, 16, v98
	v_lshlrev_b32_e32 v99, 16, v99
	v_lshlrev_b32_e32 v100, 16, v100
	s_cmp_eq_u32 s2, 0
	s_cbranch_scc1 .Lpool_w2
	s_cmp_eq_u32 s2, 1
	s_cbranch_scc1 .Lpool_w4
	s_cmp_eq_u32 s2, 2
	s_cbranch_scc1 .Lpool_w8
.Lpool_w16:
	s_mov_b32 s2, 0x3d800000
	v_add_f32_e32 v101, 0, v36
	v_add_f32_e32 v101, v101, v35
	v_add_f32_e32 v101, v101, v34
	v_add_f32_e32 v101, v101, v33
	v_add_f32_e32 v101, v101, v32
	v_add_f32_e32 v101, v101, v31
	v_add_f32_e32 v101, v101, v30
	v_add_f32_e32 v101, v101, v29
	v_add_f32_e32 v101, v101, v28
	v_add_f32_e32 v101, v101, v27
	v_add_f32_e32 v101, v101, v26
	v_add_f32_e32 v101, v101, v25
	v_add_f32_e32 v101, v101, v24
	v_add_f32_e32 v101, v101, v23
	v_add_f32_e32 v101, v101, v22
	v_add_f32_e32 v101, v101, v21
	v_sub_f32_e32 v102, v37, v21
	v_fma_f32 v103, v101, s2, -v36
	v_add_f32_e32 v101, v101, v102
	v_cvt_pk_bf16_f32 v103, v103, v17
	ds_write_b16 v105, v103 offset:0
	v_sub_f32_e32 v102, v38, v22
	v_fma_f32 v104, v101, s2, -v37
	v_add_f32_e32 v101, v101, v102
	v_cvt_pk_bf16_f32 v104, v104, v17
	ds_write_b16 v105, v104 offset:1040
	v_sub_f32_e32 v102, v39, v23
	v_fma_f32 v103, v101, s2, -v38
	v_add_f32_e32 v101, v101, v102
	v_cvt_pk_bf16_f32 v103, v103, v17
	ds_write_b16 v105, v103 offset:2080
	v_sub_f32_e32 v102, v40, v24
	v_fma_f32 v104, v101, s2, -v39
	v_add_f32_e32 v101, v101, v102
	v_cvt_pk_bf16_f32 v104, v104, v17
	ds_write_b16 v105, v104 offset:3120
	v_sub_f32_e32 v102, v41, v25
	v_fma_f32 v103, v101, s2, -v40
	v_add_f32_e32 v101, v101, v102
	v_cvt_pk_bf16_f32 v103, v103, v17
	ds_write_b16 v105, v103 offset:4160
	v_sub_f32_e32 v102, v42, v26
	v_fma_f32 v104, v101, s2, -v41
	v_add_f32_e32 v101, v101, v102
	v_cvt_pk_bf16_f32 v104, v104, v17
	ds_write_b16 v105, v104 offset:5200
	v_sub_f32_e32 v102, v43, v27
	v_fma_f32 v103, v101, s2, -v42
	v_add_f32_e32 v101, v101, v102
	v_cvt_pk_bf16_f32 v103, v103, v17
	ds_write_b16 v105, v103 offset:6240
	v_sub_f32_e32 v102, v44, v28
	v_fma_f32 v104, v101, s2, -v43
	v_add_f32_e32 v101, v101, v102
	v_cvt_pk_bf16_f32 v104, v104, v17
	ds_write_b16 v105, v104 offset:7280
	v_sub_f32_e32 v102, v45, v29
	v_fma_f32 v103, v101, s2, -v44
	v_add_f32_e32 v101, v101, v102
	v_cvt_pk_bf16_f32 v103, v103, v17
	ds_write_b16 v105, v103 offset:8320
	v_sub_f32_e32 v102, v46, v30
	v_fma_f32 v104, v101, s2, -v45
	v_add_f32_e32 v101, v101, v102
	v_cvt_pk_bf16_f32 v104, v104, v17
	ds_write_b16 v105, v104 offset:9360
	v_sub_f32_e32 v102, v47, v31
	v_fma_f32 v103, v101, s2, -v46
	v_add_f32_e32 v101, v101, v102
	v_cvt_pk_bf16_f32 v103, v103, v17
	ds_write_b16 v105, v103 offset:10400
	v_sub_f32_e32 v102, v48, v32
	v_fma_f32 v104, v101, s2, -v47
	v_add_f32_e32 v101, v101, v102
	v_cvt_pk_bf16_f32 v104, v104, v17
	ds_write_b16 v105, v104 offset:11440
	v_sub_f32_e32 v102, v49, v33
	v_fma_f32 v103, v101, s2, -v48
	v_add_f32_e32 v101, v101, v102
	v_cvt_pk_bf16_f32 v103, v103, v17
	ds_write_b16 v105, v103 offset:12480
	v_sub_f32_e32 v102, v50, v34
	v_fma_f32 v104, v101, s2, -v49
	v_add_f32_e32 v101, v101, v102
	v_cvt_pk_bf16_f32 v104, v104, v17
	ds_write_b16 v105, v104 offset:13520
	v_sub_f32_e32 v102, v51, v35
	v_fma_f32 v103, v101, s2, -v50
	v_add_f32_e32 v101, v101, v102
	v_cvt_pk_bf16_f32 v103, v103, v17
	ds_write_b16 v105, v103 offset:14560
	v_sub_f32_e32 v102, v52, v36
	v_fma_f32 v104, v101, s2, -v51
	v_add_f32_e32 v101, v101, v102
	v_cvt_pk_bf16_f32 v104, v104, v17
	ds_write_b16 v105, v104 offset:15600
	v_sub_f32_e32 v102, v53, v37
	v_fma_f32 v103, v101, s2, -v52
	v_add_f32_e32 v101, v101, v102
	v_cvt_pk_bf16_f32 v103, v103, v17
	ds_write_b16 v105, v103 offset:16640
	v_sub_f32_e32 v102, v54, v38
	v_fma_f32 v104, v101, s2, -v53
	v_add_f32_e32 v101, v101, v102
	v_cvt_pk_bf16_f32 v104, v104, v17
	ds_write_b16 v105, v104 offset:17680
	v_sub_f32_e32 v102, v55, v39
	v_fma_f32 v103, v101, s2, -v54
	v_add_f32_e32 v101, v101, v102
	v_cvt_pk_bf16_f32 v103, v103, v17
	ds_write_b16 v105, v103 offset:18720
	v_sub_f32_e32 v102, v56, v40
	v_fma_f32 v104, v101, s2, -v55
	v_add_f32_e32 v101, v101, v102
	v_cvt_pk_bf16_f32 v104, v104, v17
	ds_write_b16 v105, v104 offset:19760
	v_sub_f32_e32 v102, v57, v41
	v_fma_f32 v103, v101, s2, -v56
	v_add_f32_e32 v101, v101, v102
	v_cvt_pk_bf16_f32 v103, v103, v17
	ds_write_b16 v105, v103 offset:20800
	v_sub_f32_e32 v102, v58, v42
	v_fma_f32 v104, v101, s2, -v57
	v_add_f32_e32 v101, v101, v102
	v_cvt_pk_bf16_f32 v104, v104, v17
	ds_write_b16 v105, v104 offset:21840
	v_sub_f32_e32 v102, v59, v43
	v_fma_f32 v103, v101, s2, -v58
	v_add_f32_e32 v101, v101, v102
	v_cvt_pk_bf16_f32 v103, v103, v17
	ds_write_b16 v105, v103 offset:22880
	v_sub_f32_e32 v102, v60, v44
	v_fma_f32 v104, v101, s2, -v59
	v_add_f32_e32 v101, v101, v102
	v_cvt_pk_bf16_f32 v104, v104, v17
	ds_write_b16 v105, v104 offset:23920
	v_sub_f32_e32 v102, v61, v45
	v_fma_f32 v103, v101, s2, -v60
	v_add_f32_e32 v101, v101, v102
	v_cvt_pk_bf16_f32 v103, v103, v17
	ds_write_b16 v105, v103 offset:24960
	v_sub_f32_e32 v102, v62, v46
	v_fma_f32 v104, v101, s2, -v61
	v_add_f32_e32 v101, v101, v102
	v_cvt_pk_bf16_f32 v104, v104, v17
	ds_write_b16 v105, v104 offset:26000
	v_sub_f32_e32 v102, v63, v47
	v_fma_f32 v103, v101, s2, -v62
	v_add_f32_e32 v101, v101, v102
	v_cvt_pk_bf16_f32 v103, v103, v17
	ds_write_b16 v105, v103 offset:27040
	v_sub_f32_e32 v102, v64, v48
	v_fma_f32 v104, v101, s2, -v63
	v_add_f32_e32 v101, v101, v102
	v_cvt_pk_bf16_f32 v104, v104, v17
	ds_write_b16 v105, v104 offset:28080
	v_sub_f32_e32 v102, v65, v49
	v_fma_f32 v103, v101, s2, -v64
	v_add_f32_e32 v101, v101, v102
	v_cvt_pk_bf16_f32 v103, v103, v17
	ds_write_b16 v105, v103 offset:29120
	v_sub_f32_e32 v102, v66, v50
	v_fma_f32 v104, v101, s2, -v65
	v_add_f32_e32 v101, v101, v102
	v_cvt_pk_bf16_f32 v104, v104, v17
	ds_write_b16 v105, v104 offset:30160
	v_sub_f32_e32 v102, v67, v51
	v_fma_f32 v103, v101, s2, -v66
	v_add_f32_e32 v101, v101, v102
	v_cvt_pk_bf16_f32 v103, v103, v17
	ds_write_b16 v105, v103 offset:31200
	v_sub_f32_e32 v102, v68, v52
	v_fma_f32 v104, v101, s2, -v67
	v_add_f32_e32 v101, v101, v102
	v_cvt_pk_bf16_f32 v104, v104, v17
	ds_write_b16 v105, v104 offset:32240
	v_sub_f32_e32 v102, v69, v53
	v_fma_f32 v103, v101, s2, -v68
	v_add_f32_e32 v101, v101, v102
	v_cvt_pk_bf16_f32 v103, v103, v17
	ds_write_b16 v105, v103 offset:33280
	v_sub_f32_e32 v102, v70, v54
	v_fma_f32 v104, v101, s2, -v69
	v_add_f32_e32 v101, v101, v102
	v_cvt_pk_bf16_f32 v104, v104, v17
	ds_write_b16 v105, v104 offset:34320
	v_sub_f32_e32 v102, v71, v55
	v_fma_f32 v103, v101, s2, -v70
	v_add_f32_e32 v101, v101, v102
	v_cvt_pk_bf16_f32 v103, v103, v17
	ds_write_b16 v105, v103 offset:35360
	v_sub_f32_e32 v102, v72, v56
	v_fma_f32 v104, v101, s2, -v71
	v_add_f32_e32 v101, v101, v102
	v_cvt_pk_bf16_f32 v104, v104, v17
	ds_write_b16 v105, v104 offset:36400
	v_sub_f32_e32 v102, v73, v57
	v_fma_f32 v103, v101, s2, -v72
	v_add_f32_e32 v101, v101, v102
	v_cvt_pk_bf16_f32 v103, v103, v17
	ds_write_b16 v105, v103 offset:37440
	v_sub_f32_e32 v102, v74, v58
	v_fma_f32 v104, v101, s2, -v73
	v_add_f32_e32 v101, v101, v102
	v_cvt_pk_bf16_f32 v104, v104, v17
	ds_write_b16 v105, v104 offset:38480
	v_sub_f32_e32 v102, v75, v59
	v_fma_f32 v103, v101, s2, -v74
	v_add_f32_e32 v101, v101, v102
	v_cvt_pk_bf16_f32 v103, v103, v17
	ds_write_b16 v105, v103 offset:39520
	v_sub_f32_e32 v102, v76, v60
	v_fma_f32 v104, v101, s2, -v75
	v_add_f32_e32 v101, v101, v102
	v_cvt_pk_bf16_f32 v104, v104, v17
	ds_write_b16 v105, v104 offset:40560
	v_sub_f32_e32 v102, v77, v61
	v_fma_f32 v103, v101, s2, -v76
	v_add_f32_e32 v101, v101, v102
	v_cvt_pk_bf16_f32 v103, v103, v17
	ds_write_b16 v105, v103 offset:41600
	v_sub_f32_e32 v102, v79, v62
	v_fma_f32 v104, v101, s2, -v77
	v_add_f32_e32 v101, v101, v102
	v_cvt_pk_bf16_f32 v104, v104, v17
	ds_write_b16 v105, v104 offset:42640
	v_sub_f32_e32 v102, v80, v63
	v_fma_f32 v103, v101, s2, -v79
	v_add_f32_e32 v101, v101, v102
	v_cvt_pk_bf16_f32 v103, v103, v17
	ds_write_b16 v105, v103 offset:43680
	v_sub_f32_e32 v102, v81, v64
	v_fma_f32 v104, v101, s2, -v80
	v_add_f32_e32 v101, v101, v102
	v_cvt_pk_bf16_f32 v104, v104, v17
	ds_write_b16 v105, v104 offset:44720
	v_sub_f32_e32 v102, v82, v65
	v_fma_f32 v103, v101, s2, -v81
	v_add_f32_e32 v101, v101, v102
	v_cvt_pk_bf16_f32 v103, v103, v17
	ds_write_b16 v105, v103 offset:45760
	v_sub_f32_e32 v102, v83, v66
	v_fma_f32 v104, v101, s2, -v82
	v_add_f32_e32 v101, v101, v102
	v_cvt_pk_bf16_f32 v104, v104, v17
	ds_write_b16 v105, v104 offset:46800
	v_sub_f32_e32 v102, v84, v67
	v_fma_f32 v103, v101, s2, -v83
	v_add_f32_e32 v101, v101, v102
	v_cvt_pk_bf16_f32 v103, v103, v17
	ds_write_b16 v105, v103 offset:47840
	v_sub_f32_e32 v102, v85, v68
	v_fma_f32 v104, v101, s2, -v84
	v_add_f32_e32 v101, v101, v102
	v_cvt_pk_bf16_f32 v104, v104, v17
	ds_write_b16 v105, v104 offset:48880
	v_sub_f32_e32 v102, v86, v69
	v_fma_f32 v103, v101, s2, -v85
	v_add_f32_e32 v101, v101, v102
	v_cvt_pk_bf16_f32 v103, v103, v17
	ds_write_b16 v105, v103 offset:49920
	v_sub_f32_e32 v102, v87, v70
	v_fma_f32 v104, v101, s2, -v86
	v_add_f32_e32 v101, v101, v102
	v_cvt_pk_bf16_f32 v104, v104, v17
	ds_write_b16 v105, v104 offset:50960
	v_sub_f32_e32 v102, v88, v71
	v_fma_f32 v103, v101, s2, -v87
	v_add_f32_e32 v101, v101, v102
	v_cvt_pk_bf16_f32 v103, v103, v17
	ds_write_b16 v105, v103 offset:52000
	v_sub_f32_e32 v102, v89, v72
	v_fma_f32 v104, v101, s2, -v88
	v_add_f32_e32 v101, v101, v102
	v_cvt_pk_bf16_f32 v104, v104, v17
	ds_write_b16 v105, v104 offset:53040
	v_sub_f32_e32 v102, v90, v73
	v_fma_f32 v103, v101, s2, -v89
	v_add_f32_e32 v101, v101, v102
	v_cvt_pk_bf16_f32 v103, v103, v17
	ds_write_b16 v105, v103 offset:54080
	v_sub_f32_e32 v102, v91, v74
	v_fma_f32 v104, v101, s2, -v90
	v_add_f32_e32 v101, v101, v102
	v_cvt_pk_bf16_f32 v104, v104, v17
	ds_write_b16 v105, v104 offset:55120
	v_sub_f32_e32 v102, v92, v75
	v_fma_f32 v103, v101, s2, -v91
	v_add_f32_e32 v101, v101, v102
	v_cvt_pk_bf16_f32 v103, v103, v17
	ds_write_b16 v105, v103 offset:56160
	v_sub_f32_e32 v102, v93, v76
	v_fma_f32 v104, v101, s2, -v92
	v_add_f32_e32 v101, v101, v102
	v_cvt_pk_bf16_f32 v104, v104, v17
	ds_write_b16 v105, v104 offset:57200
	v_sub_f32_e32 v102, v94, v77
	v_fma_f32 v103, v101, s2, -v93
	v_add_f32_e32 v101, v101, v102
	v_cvt_pk_bf16_f32 v103, v103, v17
	ds_write_b16 v105, v103 offset:58240
	v_sub_f32_e32 v102, v95, v79
	v_fma_f32 v104, v101, s2, -v94
	v_add_f32_e32 v101, v101, v102
	v_cvt_pk_bf16_f32 v104, v104, v17
	ds_write_b16 v105, v104 offset:59280
	v_sub_f32_e32 v102, v96, v80
	v_fma_f32 v103, v101, s2, -v95
	v_add_f32_e32 v101, v101, v102
	v_cvt_pk_bf16_f32 v103, v103, v17
	ds_write_b16 v105, v103 offset:60320
	v_sub_f32_e32 v102, v97, v81
	v_fma_f32 v104, v101, s2, -v96
	v_add_f32_e32 v101, v101, v102
	v_cvt_pk_bf16_f32 v104, v104, v17
	ds_write_b16 v105, v104 offset:61360
	v_sub_f32_e32 v102, v98, v82
	v_fma_f32 v103, v101, s2, -v97
	v_add_f32_e32 v101, v101, v102
	v_cvt_pk_bf16_f32 v103, v103, v17
	ds_write_b16 v105, v103 offset:62400
	v_sub_f32_e32 v102, v99, v83
	v_fma_f32 v104, v101, s2, -v98
	v_add_f32_e32 v101, v101, v102
	v_cvt_pk_bf16_f32 v104, v104, v17
	ds_write_b16 v105, v104 offset:63440
	v_sub_f32_e32 v102, v100, v84
	v_fma_f32 v103, v101, s2, -v99
	v_add_f32_e32 v101, v101, v102
	v_cvt_pk_bf16_f32 v103, v103, v17
	ds_write_b16 v105, v103 offset:64480
	v_fma_f32 v104, v101, s2, -v100
	v_cvt_pk_bf16_f32 v104, v104, v17
	ds_write_b16 v105, v104 offset:65520
	v_mov_b32_e32 v1, v104
	s_branch .Lpool_join
.Lpool_w8:
	s_mov_b32 s2, 0x3e000000
	v_add_f32_e32 v101, 0, v36
	v_add_f32_e32 v101, v101, v35
	v_add_f32_e32 v101, v101, v34
	v_add_f32_e32 v101, v101, v33
	v_add_f32_e32 v101, v101, v32
	v_add_f32_e32 v101, v101, v31
	v_add_f32_e32 v101, v101, v30
	v_add_f32_e32 v101, v101, v29
	v_sub_f32_e32 v102, v37, v29
	v_fma_f32 v103, v101, s2, -v36
	v_add_f32_e32 v101, v101, v102
	v_cvt_pk_bf16_f32 v103, v103, v17
	ds_write_b16 v105, v103 offset:0
	v_sub_f32_e32 v102, v38, v30
	v_fma_f32 v104, v101, s2, -v37
	v_add_f32_e32 v101, v101, v102
	v_cvt_pk_bf16_f32 v104, v104, v17
	ds_write_b16 v105, v104 offset:1040
	v_sub_f32_e32 v102, v39, v31
	v_fma_f32 v103, v101, s2, -v38
	v_add_f32_e32 v101, v101, v102
	v_cvt_pk_bf16_f32 v103, v103, v17
	ds_write_b16 v105, v103 offset:2080
	v_sub_f32_e32 v102, v40, v32
	v_fma_f32 v104, v101, s2, -v39
	v_add_f32_e32 v101, v101, v102
	v_cvt_pk_bf16_f32 v104, v104, v17
	ds_write_b16 v105, v104 offset:3120
	v_sub_f32_e32 v102, v41, v33
	v_fma_f32 v103, v101, s2, -v40
	v_add_f32_e32 v101, v101, v102
	v_cvt_pk_bf16_f32 v103, v103, v17
	ds_write_b16 v105, v103 offset:4160
	v_sub_f32_e32 v102, v42, v34
	v_fma_f32 v104, v101, s2, -v41
	v_add_f32_e32 v101, v101, v102
	v_cvt_pk_bf16_f32 v104, v104, v17
	ds_write_b16 v105, v104 offset:5200
	v_sub_f32_e32 v102, v43, v35
	v_fma_f32 v103, v101, s2, -v42
	v_add_f32_e32 v101, v101, v102
	v_cvt_pk_bf16_f32 v103, v103, v17
	ds_write_b16 v105, v103 offset:6240
	v_sub_f32_e32 v102, v44, v36
	v_fma_f32 v104, v101, s2, -v43
	v_add_f32_e32 v101, v101, v102
	v_cvt_pk_bf16_f32 v104, v104, v17
	ds_write_b16 v105, v104 offset:7280
	v_sub_f32_e32 v102, v45, v37
	v_fma_f32 v103, v101, s2, -v44
	v_add_f32_e32 v101, v101, v102
	v_cvt_pk_bf16_f32 v103, v103, v17
	ds_write_b16 v105, v103 offset:8320
	v_sub_f32_e32 v102, v46, v38
	v_fma_f32 v104, v101, s2, -v45
	v_add_f32_e32 v101, v101, v102
	v_cvt_pk_bf16_f32 v104, v104, v17
	ds_write_b16 v105, v104 offset:9360
	v_sub_f32_e32 v102, v47, v39
	v_fma_f32 v103, v101, s2, -v46
	v_add_f32_e32 v101, v101, v102
	v_cvt_pk_bf16_f32 v103, v103, v17
	ds_write_b16 v105, v103 offset:10400
	v_sub_f32_e32 v102, v48, v40
	v_fma_f32 v104, v101, s2, -v47
	v_add_f32_e32 v101, v101, v102
	v_cvt_pk_bf16_f32 v104, v104, v17
	ds_write_b16 v105, v104 offset:11440
	v_sub_f32_e32 v102, v49, v41
	v_fma_f32 v103, v101, s2, -v48
	v_add_f32_e32 v101, v101, v102
	v_cvt_pk_bf16_f32 v103, v103, v17
	ds_write_b16 v105, v103 offset:12480
	v_sub_f32_e32 v102, v50, v42
	v_fma_f32 v104, v101, s2, -v49
	v_add_f32_e32 v101, v101, v102
	v_cvt_pk_bf16_f32 v104, v104, v17
	ds_write_b16 v105, v104 offset:13520
	v_sub_f32_e32 v102, v51, v43
	v_fma_f32 v103, v101, s2, -v50
	v_add_f32_e32 v101, v101, v102
	v_cvt_pk_bf16_f32 v103, v103, v17
	ds_write_b16 v105, v103 offset:14560
	v_sub_f32_e32 v102, v52, v44
	v_fma_f32 v104, v101, s2, -v51
	v_add_f32_e32 v101, v101, v102
	v_cvt_pk_bf16_f32 v104, v104, v17
	ds_write_b16 v105, v104 offset:15600
	v_sub_f32_e32 v102, v53, v45
	v_fma_f32 v103, v101, s2, -v52
	v_add_f32_e32 v101, v101, v102
	v_cvt_pk_bf16_f32 v103, v103, v17
	ds_write_b16 v105, v103 offset:16640
	v_sub_f32_e32 v102, v54, v46
	v_fma_f32 v104, v101, s2, -v53
	v_add_f32_e32 v101, v101, v102
	v_cvt_pk_bf16_f32 v104, v104, v17
	ds_write_b16 v105, v104 offset:17680
	v_sub_f32_e32 v102, v55, v47
	v_fma_f32 v103, v101, s2, -v54
	v_add_f32_e32 v101, v101, v102
	v_cvt_pk_bf16_f32 v103, v103, v17
	ds_write_b16 v105, v103 offset:18720
	v_sub_f32_e32 v102, v56, v48
	v_fma_f32 v104, v101, s2, -v55
	v_add_f32_e32 v101, v101, v102
	v_cvt_pk_bf16_f32 v104, v104, v17
	ds_write_b16 v105, v104 offset:19760
	v_sub_f32_e32 v102, v57, v49
	v_fma_f32 v103, v101, s2, -v56
	v_add_f32_e32 v101, v101, v102
	v_cvt_pk_bf16_f32 v103, v103, v17
	ds_write_b16 v105, v103 offset:20800
	v_sub_f32_e32 v102, v58, v50
	v_fma_f32 v104, v101, s2, -v57
	v_add_f32_e32 v101, v101, v102
	v_cvt_pk_bf16_f32 v104, v104, v17
	ds_write_b16 v105, v104 offset:21840
	v_sub_f32_e32 v102, v59, v51
	v_fma_f32 v103, v101, s2, -v58
	v_add_f32_e32 v101, v101, v102
	v_cvt_pk_bf16_f32 v103, v103, v17
	ds_write_b16 v105, v103 offset:22880
	v_sub_f32_e32 v102, v60, v52
	v_fma_f32 v104, v101, s2, -v59
	v_add_f32_e32 v101, v101, v102
	v_cvt_pk_bf16_f32 v104, v104, v17
	ds_write_b16 v105, v104 offset:23920
	v_sub_f32_e32 v102, v61, v53
	v_fma_f32 v103, v101, s2, -v60
	v_add_f32_e32 v101, v101, v102
	v_cvt_pk_bf16_f32 v103, v103, v17
	ds_write_b16 v105, v103 offset:24960
	v_sub_f32_e32 v102, v62, v54
	v_fma_f32 v104, v101, s2, -v61
	v_add_f32_e32 v101, v101, v102
	v_cvt_pk_bf16_f32 v104, v104, v17
	ds_write_b16 v105, v104 offset:26000
	v_sub_f32_e32 v102, v63, v55
	v_fma_f32 v103, v101, s2, -v62
	v_add_f32_e32 v101, v101, v102
	v_cvt_pk_bf16_f32 v103, v103, v17
	ds_write_b16 v105, v103 offset:27040
	v_sub_f32_e32 v102, v64, v56
	v_fma_f32 v104, v101, s2, -v63
	v_add_f32_e32 v101, v101, v102
	v_cvt_pk_bf16_f32 v104, v104, v17
	ds_write_b16 v105, v104 offset:28080
	v_sub_f32_e32 v102, v65, v57
	v_fma_f32 v103, v101, s2, -v64
	v_add_f32_e32 v101, v101, v102
	v_cvt_pk_bf16_f32 v103, v103, v17
	ds_write_b16 v105, v103 offset:29120
	v_sub_f32_e32 v102, v66, v58
	v_fma_f32 v104, v101, s2, -v65
	v_add_f32_e32 v101, v101, v102
	v_cvt_pk_bf16_f32 v104, v104, v17
	ds_write_b16 v105, v104 offset:30160
	v_sub_f32_e32 v102, v67, v59
	v_fma_f32 v103, v101, s2, -v66
	v_add_f32_e32 v101, v101, v102
	v_cvt_pk_bf16_f32 v103, v103, v17
	ds_write_b16 v105, v103 offset:31200
	v_sub_f32_e32 v102, v68, v60
	v_fma_f32 v104, v101, s2, -v67
	v_add_f32_e32 v101, v101, v102
	v_cvt_pk_bf16_f32 v104, v104, v17
	ds_write_b16 v105, v104 offset:32240
	v_sub_f32_e32 v102, v69, v61
	v_fma_f32 v103, v101, s2, -v68
	v_add_f32_e32 v101, v101, v102
	v_cvt_pk_bf16_f32 v103, v103, v17
	ds_write_b16 v105, v103 offset:33280
	v_sub_f32_e32 v102, v70, v62
	v_fma_f32 v104, v101, s2, -v69
	v_add_f32_e32 v101, v101, v102
	v_cvt_pk_bf16_f32 v104, v104, v17
	ds_write_b16 v105, v104 offset:34320
	v_sub_f32_e32 v102, v71, v63
	v_fma_f32 v103, v101, s2, -v70
	v_add_f32_e32 v101, v101, v102
	v_cvt_pk_bf16_f32 v103, v103, v17
	ds_write_b16 v105, v103 offset:35360
	v_sub_f32_e32 v102, v72, v64
	v_fma_f32 v104, v101, s2, -v71
	v_add_f32_e32 v101, v101, v102
	v_cvt_pk_bf16_f32 v104, v104, v17
	ds_write_b16 v105, v104 offset:36400
	v_sub_f32_e32 v102, v73, v65
	v_fma_f32 v103, v101, s2, -v72
	v_add_f32_e32 v101, v101, v102
	v_cvt_pk_bf16_f32 v103, v103, v17
	ds_write_b16 v105, v103 offset:37440
	v_sub_f32_e32 v102, v74, v66
	v_fma_f32 v104, v101, s2, -v73
	v_add_f32_e32 v101, v101, v102
	v_cvt_pk_bf16_f32 v104, v104, v17
	ds_write_b16 v105, v104 offset:38480
	v_sub_f32_e32 v102, v75, v67
	v_fma_f32 v103, v101, s2, -v74
	v_add_f32_e32 v101, v101, v102
	v_cvt_pk_bf16_f32 v103, v103, v17
	ds_write_b16 v105, v103 offset:39520
	v_sub_f32_e32 v102, v76, v68
	v_fma_f32 v104, v101, s2, -v75
	v_add_f32_e32 v101, v101, v102
	v_cvt_pk_bf16_f32 v104, v104, v17
	ds_write_b16 v105, v104 offset:40560
	v_sub_f32_e32 v102, v77, v69
	v_fma_f32 v103, v101, s2, -v76
	v_add_f32_e32 v101, v101, v102
	v_cvt_pk_bf16_f32 v103, v103, v17
	ds_write_b16 v105, v103 offset:41600
	v_sub_f32_e32 v102, v79, v70
	v_fma_f32 v104, v101, s2, -v77
	v_add_f32_e32 v101, v101, v102
	v_cvt_pk_bf16_f32 v104, v104, v17
	ds_write_b16 v105, v104 offset:42640
	v_sub_f32_e32 v102, v80, v71
	v_fma_f32 v103, v101, s2, -v79
	v_add_f32_e32 v101, v101, v102
	v_cvt_pk_bf16_f32 v103, v103, v17
	ds_write_b16 v105, v103 offset:43680
	v_sub_f32_e32 v102, v81, v72
	v_fma_f32 v104, v101, s2, -v80
	v_add_f32_e32 v101, v101, v102
	v_cvt_pk_bf16_f32 v104, v104, v17
	ds_write_b16 v105, v104 offset:44720
	v_sub_f32_e32 v102, v82, v73
	v_fma_f32 v103, v101, s2, -v81
	v_add_f32_e32 v101, v101, v102
	v_cvt_pk_bf16_f32 v103, v103, v17
	ds_write_b16 v105, v103 offset:45760
	v_sub_f32_e32 v102, v83, v74
	v_fma_f32 v104, v101, s2, -v82
	v_add_f32_e32 v101, v101, v102
	v_cvt_pk_bf16_f32 v104, v104, v17
	ds_write_b16 v105, v104 offset:46800
	v_sub_f32_e32 v102, v84, v75
	v_fma_f32 v103, v101, s2, -v83
	v_add_f32_e32 v101, v101, v102
	v_cvt_pk_bf16_f32 v103, v103, v17
	ds_write_b16 v105, v103 offset:47840
	v_sub_f32_e32 v102, v85, v76
	v_fma_f32 v104, v101, s2, -v84
	v_add_f32_e32 v101, v101, v102
	v_cvt_pk_bf16_f32 v104, v104, v17
	ds_write_b16 v105, v104 offset:48880
	v_sub_f32_e32 v102, v86, v77
	v_fma_f32 v103, v101, s2, -v85
	v_add_f32_e32 v101, v101, v102
	v_cvt_pk_bf16_f32 v103, v103, v17
	ds_write_b16 v105, v103 offset:49920
	v_sub_f32_e32 v102, v87, v79
	v_fma_f32 v104, v101, s2, -v86
	v_add_f32_e32 v101, v101, v102
	v_cvt_pk_bf16_f32 v104, v104, v17
	ds_write_b16 v105, v104 offset:50960
	v_sub_f32_e32 v102, v88, v80
	v_fma_f32 v103, v101, s2, -v87
	v_add_f32_e32 v101, v101, v102
	v_cvt_pk_bf16_f32 v103, v103, v17
	ds_write_b16 v105, v103 offset:52000
	v_sub_f32_e32 v102, v89, v81
	v_fma_f32 v104, v101, s2, -v88
	v_add_f32_e32 v101, v101, v102
	v_cvt_pk_bf16_f32 v104, v104, v17
	ds_write_b16 v105, v104 offset:53040
	v_sub_f32_e32 v102, v90, v82
	v_fma_f32 v103, v101, s2, -v89
	v_add_f32_e32 v101, v101, v102
	v_cvt_pk_bf16_f32 v103, v103, v17
	ds_write_b16 v105, v103 offset:54080
	v_sub_f32_e32 v102, v91, v83
	v_fma_f32 v104, v101, s2, -v90
	v_add_f32_e32 v101, v101, v102
	v_cvt_pk_bf16_f32 v104, v104, v17
	ds_write_b16 v105, v104 offset:55120
	v_sub_f32_e32 v102, v92, v84
	v_fma_f32 v103, v101, s2, -v91
	v_add_f32_e32 v101, v101, v102
	v_cvt_pk_bf16_f32 v103, v103, v17
	ds_write_b16 v105, v103 offset:56160
	v_sub_f32_e32 v102, v93, v85
	v_fma_f32 v104, v101, s2, -v92
	v_add_f32_e32 v101, v101, v102
	v_cvt_pk_bf16_f32 v104, v104, v17
	ds_write_b16 v105, v104 offset:57200
	v_sub_f32_e32 v102, v94, v86
	v_fma_f32 v103, v101, s2, -v93
	v_add_f32_e32 v101, v101, v102
	v_cvt_pk_bf16_f32 v103, v103, v17
	ds_write_b16 v105, v103 offset:58240
	v_sub_f32_e32 v102, v95, v87
	v_fma_f32 v104, v101, s2, -v94
	v_add_f32_e32 v101, v101, v102
	v_cvt_pk_bf16_f32 v104, v104, v17
	ds_write_b16 v105, v104 offset:59280
	v_sub_f32_e32 v102, v96, v88
	v_fma_f32 v103, v101, s2, -v95
	v_add_f32_e32 v101, v101, v102
	v_cvt_pk_bf16_f32 v103, v103, v17
	ds_write_b16 v105, v103 offset:60320
	v_sub_f32_e32 v102, v97, v89
	v_fma_f32 v104, v101, s2, -v96
	v_add_f32_e32 v101, v101, v102
	v_cvt_pk_bf16_f32 v104, v104, v17
	ds_write_b16 v105, v104 offset:61360
	v_sub_f32_e32 v102, v98, v90
	v_fma_f32 v103, v101, s2, -v97
	v_add_f32_e32 v101, v101, v102
	v_cvt_pk_bf16_f32 v103, v103, v17
	ds_write_b16 v105, v103 offset:62400
	v_sub_f32_e32 v102, v99, v91
	v_fma_f32 v104, v101, s2, -v98
	v_add_f32_e32 v101, v101, v102
	v_cvt_pk_bf16_f32 v104, v104, v17
	ds_write_b16 v105, v104 offset:63440
	v_sub_f32_e32 v102, v100, v92
	v_fma_f32 v103, v101, s2, -v99
	v_add_f32_e32 v101, v101, v102
	v_cvt_pk_bf16_f32 v103, v103, v17
	ds_write_b16 v105, v103 offset:64480
	v_fma_f32 v104, v101, s2, -v100
	v_cvt_pk_bf16_f32 v104, v104, v17
	ds_write_b16 v105, v104 offset:65520
	v_mov_b32_e32 v1, v104
	s_branch .Lpool_join
.Lpool_w4:
	s_mov_b32 s2, 0x3e800000
	v_add_f32_e32 v101, 0, v36
	v_add_f32_e32 v101, v101, v35
	v_add_f32_e32 v101, v101, v34
	v_add_f32_e32 v101, v101, v33
	v_sub_f32_e32 v102, v37, v33
	v_fma_f32 v103, v101, s2, -v36
	v_add_f32_e32 v101, v101, v102
	v_cvt_pk_bf16_f32 v103, v103, v17
	ds_write_b16 v105, v103 offset:0
	v_sub_f32_e32 v102, v38, v34
	v_fma_f32 v104, v101, s2, -v37
	v_add_f32_e32 v101, v101, v102
	v_cvt_pk_bf16_f32 v104, v104, v17
	ds_write_b16 v105, v104 offset:1040
	v_sub_f32_e32 v102, v39, v35
	v_fma_f32 v103, v101, s2, -v38
	v_add_f32_e32 v101, v101, v102
	v_cvt_pk_bf16_f32 v103, v103, v17
	ds_write_b16 v105, v103 offset:2080
	v_sub_f32_e32 v102, v40, v36
	v_fma_f32 v104, v101, s2, -v39
	v_add_f32_e32 v101, v101, v102
	v_cvt_pk_bf16_f32 v104, v104, v17
	ds_write_b16 v105, v104 offset:3120
	v_sub_f32_e32 v102, v41, v37
	v_fma_f32 v103, v101, s2, -v40
	v_add_f32_e32 v101, v101, v102
	v_cvt_pk_bf16_f32 v103, v103, v17
	ds_write_b16 v105, v103 offset:4160
	v_sub_f32_e32 v102, v42, v38
	v_fma_f32 v104, v101, s2, -v41
	v_add_f32_e32 v101, v101, v102
	v_cvt_pk_bf16_f32 v104, v104, v17
	ds_write_b16 v105, v104 offset:5200
	v_sub_f32_e32 v102, v43, v39
	v_fma_f32 v103, v101, s2, -v42
	v_add_f32_e32 v101, v101, v102
	v_cvt_pk_bf16_f32 v103, v103, v17
	ds_write_b16 v105, v103 offset:6240
	v_sub_f32_e32 v102, v44, v40
	v_fma_f32 v104, v101, s2, -v43
	v_add_f32_e32 v101, v101, v102
	v_cvt_pk_bf16_f32 v104, v104, v17
	ds_write_b16 v105, v104 offset:7280
	v_sub_f32_e32 v102, v45, v41
	v_fma_f32 v103, v101, s2, -v44
	v_add_f32_e32 v101, v101, v102
	v_cvt_pk_bf16_f32 v103, v103, v17
	ds_write_b16 v105, v103 offset:8320
	v_sub_f32_e32 v102, v46, v42
	v_fma_f32 v104, v101, s2, -v45
	v_add_f32_e32 v101, v101, v102
	v_cvt_pk_bf16_f32 v104, v104, v17
	ds_write_b16 v105, v104 offset:9360
	v_sub_f32_e32 v102, v47, v43
	v_fma_f32 v103, v101, s2, -v46
	v_add_f32_e32 v101, v101, v102
	v_cvt_pk_bf16_f32 v103, v103, v17
	ds_write_b16 v105, v103 offset:10400
	v_sub_f32_e32 v102, v48, v44
	v_fma_f32 v104, v101, s2, -v47
	v_add_f32_e32 v101, v101, v102
	v_cvt_pk_bf16_f32 v104, v104, v17
	ds_write_b16 v105, v104 offset:11440
	v_sub_f32_e32 v102, v49, v45
	v_fma_f32 v103, v101, s2, -v48
	v_add_f32_e32 v101, v101, v102
	v_cvt_pk_bf16_f32 v103, v103, v17
	ds_write_b16 v105, v103 offset:12480
	v_sub_f32_e32 v102, v50, v46
	v_fma_f32 v104, v101, s2, -v49
	v_add_f32_e32 v101, v101, v102
	v_cvt_pk_bf16_f32 v104, v104, v17
	ds_write_b16 v105, v104 offset:13520
	v_sub_f32_e32 v102, v51, v47
	v_fma_f32 v103, v101, s2, -v50
	v_add_f32_e32 v101, v101, v102
	v_cvt_pk_bf16_f32 v103, v103, v17
	ds_write_b16 v105, v103 offset:14560
	v_sub_f32_e32 v102, v52, v48
	v_fma_f32 v104, v101, s2, -v51
	v_add_f32_e32 v101, v101, v102
	v_cvt_pk_bf16_f32 v104, v104, v17
	ds_write_b16 v105, v104 offset:15600
	v_sub_f32_e32 v102, v53, v49
	v_fma_f32 v103, v101, s2, -v52
	v_add_f32_e32 v101, v101, v102
	v_cvt_pk_bf16_f32 v103, v103, v17
	ds_write_b16 v105, v103 offset:16640
	v_sub_f32_e32 v102, v54, v50
	v_fma_f32 v104, v101, s2, -v53
	v_add_f32_e32 v101, v101, v102
	v_cvt_pk_bf16_f32 v104, v104, v17
	ds_write_b16 v105, v104 offset:17680
	v_sub_f32_e32 v102, v55, v51
	v_fma_f32 v103, v101, s2, -v54
	v_add_f32_e32 v101, v101, v102
	v_cvt_pk_bf16_f32 v103, v103, v17
	ds_write_b16 v105, v103 offset:18720
	v_sub_f32_e32 v102, v56, v52
	v_fma_f32 v104, v101, s2, -v55
	v_add_f32_e32 v101, v101, v102
	v_cvt_pk_bf16_f32 v104, v104, v17
	ds_write_b16 v105, v104 offset:19760
	v_sub_f32_e32 v102, v57, v53
	v_fma_f32 v103, v101, s2, -v56
	v_add_f32_e32 v101, v101, v102
	v_cvt_pk_bf16_f32 v103, v103, v17
	ds_write_b16 v105, v103 offset:20800
	v_sub_f32_e32 v102, v58, v54
	v_fma_f32 v104, v101, s2, -v57
	v_add_f32_e32 v101, v101, v102
	v_cvt_pk_bf16_f32 v104, v104, v17
	ds_write_b16 v105, v104 offset:21840
	v_sub_f32_e32 v102, v59, v55
	v_fma_f32 v103, v101, s2, -v58
	v_add_f32_e32 v101, v101, v102
	v_cvt_pk_bf16_f32 v103, v103, v17
	ds_write_b16 v105, v103 offset:22880
	v_sub_f32_e32 v102, v60, v56
	v_fma_f32 v104, v101, s2, -v59
	v_add_f32_e32 v101, v101, v102
	v_cvt_pk_bf16_f32 v104, v104, v17
	ds_write_b16 v105, v104 offset:23920
	v_sub_f32_e32 v102, v61, v57
	v_fma_f32 v103, v101, s2, -v60
	v_add_f32_e32 v101, v101, v102
	v_cvt_pk_bf16_f32 v103, v103, v17
	ds_write_b16 v105, v103 offset:24960
	v_sub_f32_e32 v102, v62, v58
	v_fma_f32 v104, v101, s2, -v61
	v_add_f32_e32 v101, v101, v102
	v_cvt_pk_bf16_f32 v104, v104, v17
	ds_write_b16 v105, v104 offset:26000
	v_sub_f32_e32 v102, v63, v59
	v_fma_f32 v103, v101, s2, -v62
	v_add_f32_e32 v101, v101, v102
	v_cvt_pk_bf16_f32 v103, v103, v17
	ds_write_b16 v105, v103 offset:27040
	v_sub_f32_e32 v102, v64, v60
	v_fma_f32 v104, v101, s2, -v63
	v_add_f32_e32 v101, v101, v102
	v_cvt_pk_bf16_f32 v104, v104, v17
	ds_write_b16 v105, v104 offset:28080
	v_sub_f32_e32 v102, v65, v61
	v_fma_f32 v103, v101, s2, -v64
	v_add_f32_e32 v101, v101, v102
	v_cvt_pk_bf16_f32 v103, v103, v17
	ds_write_b16 v105, v103 offset:29120
	v_sub_f32_e32 v102, v66, v62
	v_fma_f32 v104, v101, s2, -v65
	v_add_f32_e32 v101, v101, v102
	v_cvt_pk_bf16_f32 v104, v104, v17
	ds_write_b16 v105, v104 offset:30160
	v_sub_f32_e32 v102, v67, v63
	v_fma_f32 v103, v101, s2, -v66
	v_add_f32_e32 v101, v101, v102
	v_cvt_pk_bf16_f32 v103, v103, v17
	ds_write_b16 v105, v103 offset:31200
	v_sub_f32_e32 v102, v68, v64
	v_fma_f32 v104, v101, s2, -v67
	v_add_f32_e32 v101, v101, v102
	v_cvt_pk_bf16_f32 v104, v104, v17
	ds_write_b16 v105, v104 offset:32240
	v_sub_f32_e32 v102, v69, v65
	v_fma_f32 v103, v101, s2, -v68
	v_add_f32_e32 v101, v101, v102
	v_cvt_pk_bf16_f32 v103, v103, v17
	ds_write_b16 v105, v103 offset:33280
	v_sub_f32_e32 v102, v70, v66
	v_fma_f32 v104, v101, s2, -v69
	v_add_f32_e32 v101, v101, v102
	v_cvt_pk_bf16_f32 v104, v104, v17
	ds_write_b16 v105, v104 offset:34320
	v_sub_f32_e32 v102, v71, v67
	v_fma_f32 v103, v101, s2, -v70
	v_add_f32_e32 v101, v101, v102
	v_cvt_pk_bf16_f32 v103, v103, v17
	ds_write_b16 v105, v103 offset:35360
	v_sub_f32_e32 v102, v72, v68
	v_fma_f32 v104, v101, s2, -v71
	v_add_f32_e32 v101, v101, v102
	v_cvt_pk_bf16_f32 v104, v104, v17
	ds_write_b16 v105, v104 offset:36400
	v_sub_f32_e32 v102, v73, v69
	v_fma_f32 v103, v101, s2, -v72
	v_add_f32_e32 v101, v101, v102
	v_cvt_pk_bf16_f32 v103, v103, v17
	ds_write_b16 v105, v103 offset:37440
	v_sub_f32_e32 v102, v74, v70
	v_fma_f32 v104, v101, s2, -v73
	v_add_f32_e32 v101, v101, v102
	v_cvt_pk_bf16_f32 v104, v104, v17
	ds_write_b16 v105, v104 offset:38480
	v_sub_f32_e32 v102, v75, v71
	v_fma_f32 v103, v101, s2, -v74
	v_add_f32_e32 v101, v101, v102
	v_cvt_pk_bf16_f32 v103, v103, v17
	ds_write_b16 v105, v103 offset:39520
	v_sub_f32_e32 v102, v76, v72
	v_fma_f32 v104, v101, s2, -v75
	v_add_f32_e32 v101, v101, v102
	v_cvt_pk_bf16_f32 v104, v104, v17
	ds_write_b16 v105, v104 offset:40560
	v_sub_f32_e32 v102, v77, v73
	v_fma_f32 v103, v101, s2, -v76
	v_add_f32_e32 v101, v101, v102
	v_cvt_pk_bf16_f32 v103, v103, v17
	ds_write_b16 v105, v103 offset:41600
	v_sub_f32_e32 v102, v79, v74
	v_fma_f32 v104, v101, s2, -v77
	v_add_f32_e32 v101, v101, v102
	v_cvt_pk_bf16_f32 v104, v104, v17
	ds_write_b16 v105, v104 offset:42640
	v_sub_f32_e32 v102, v80, v75
	v_fma_f32 v103, v101, s2, -v79
	v_add_f32_e32 v101, v101, v102
	v_cvt_pk_bf16_f32 v103, v103, v17
	ds_write_b16 v105, v103 offset:43680
	v_sub_f32_e32 v102, v81, v76
	v_fma_f32 v104, v101, s2, -v80
	v_add_f32_e32 v101, v101, v102
	v_cvt_pk_bf16_f32 v104, v104, v17
	ds_write_b16 v105, v104 offset:44720
	v_sub_f32_e32 v102, v82, v77
	v_fma_f32 v103, v101, s2, -v81
	v_add_f32_e32 v101, v101, v102
	v_cvt_pk_bf16_f32 v103, v103, v17
	ds_write_b16 v105, v103 offset:45760
	v_sub_f32_e32 v102, v83, v79
	v_fma_f32 v104, v101, s2, -v82
	v_add_f32_e32 v101, v101, v102
	v_cvt_pk_bf16_f32 v104, v104, v17
	ds_write_b16 v105, v104 offset:46800
	v_sub_f32_e32 v102, v84, v80
	v_fma_f32 v103, v101, s2, -v83
	v_add_f32_e32 v101, v101, v102
	v_cvt_pk_bf16_f32 v103, v103, v17
	ds_write_b16 v105, v103 offset:47840
	v_sub_f32_e32 v102, v85, v81
	v_fma_f32 v104, v101, s2, -v84
	v_add_f32_e32 v101, v101, v102
	v_cvt_pk_bf16_f32 v104, v104, v17
	ds_write_b16 v105, v104 offset:48880
	v_sub_f32_e32 v102, v86, v82
	v_fma_f32 v103, v101, s2, -v85
	v_add_f32_e32 v101, v101, v102
	v_cvt_pk_bf16_f32 v103, v103, v17
	ds_write_b16 v105, v103 offset:49920
	v_sub_f32_e32 v102, v87, v83
	v_fma_f32 v104, v101, s2, -v86
	v_add_f32_e32 v101, v101, v102
	v_cvt_pk_bf16_f32 v104, v104, v17
	ds_write_b16 v105, v104 offset:50960
	v_sub_f32_e32 v102, v88, v84
	v_fma_f32 v103, v101, s2, -v87
	v_add_f32_e32 v101, v101, v102
	v_cvt_pk_bf16_f32 v103, v103, v17
	ds_write_b16 v105, v103 offset:52000
	v_sub_f32_e32 v102, v89, v85
	v_fma_f32 v104, v101, s2, -v88
	v_add_f32_e32 v101, v101, v102
	v_cvt_pk_bf16_f32 v104, v104, v17
	ds_write_b16 v105, v104 offset:53040
	v_sub_f32_e32 v102, v90, v86
	v_fma_f32 v103, v101, s2, -v89
	v_add_f32_e32 v101, v101, v102
	v_cvt_pk_bf16_f32 v103, v103, v17
	ds_write_b16 v105, v103 offset:54080
	v_sub_f32_e32 v102, v91, v87
	v_fma_f32 v104, v101, s2, -v90
	v_add_f32_e32 v101, v101, v102
	v_cvt_pk_bf16_f32 v104, v104, v17
	ds_write_b16 v105, v104 offset:55120
	v_sub_f32_e32 v102, v92, v88
	v_fma_f32 v103, v101, s2, -v91
	v_add_f32_e32 v101, v101, v102
	v_cvt_pk_bf16_f32 v103, v103, v17
	ds_write_b16 v105, v103 offset:56160
	v_sub_f32_e32 v102, v93, v89
	v_fma_f32 v104, v101, s2, -v92
	v_add_f32_e32 v101, v101, v102
	v_cvt_pk_bf16_f32 v104, v104, v17
	ds_write_b16 v105, v104 offset:57200
	v_sub_f32_e32 v102, v94, v90
	v_fma_f32 v103, v101, s2, -v93
	v_add_f32_e32 v101, v101, v102
	v_cvt_pk_bf16_f32 v103, v103, v17
	ds_write_b16 v105, v103 offset:58240
	v_sub_f32_e32 v102, v95, v91
	v_fma_f32 v104, v101, s2, -v94
	v_add_f32_e32 v101, v101, v102
	v_cvt_pk_bf16_f32 v104, v104, v17
	ds_write_b16 v105, v104 offset:59280
	v_sub_f32_e32 v102, v96, v92
	v_fma_f32 v103, v101, s2, -v95
	v_add_f32_e32 v101, v101, v102
	v_cvt_pk_bf16_f32 v103, v103, v17
	ds_write_b16 v105, v103 offset:60320
	v_sub_f32_e32 v102, v97, v93
	v_fma_f32 v104, v101, s2, -v96
	v_add_f32_e32 v101, v101, v102
	v_cvt_pk_bf16_f32 v104, v104, v17
	ds_write_b16 v105, v104 offset:61360
	v_sub_f32_e32 v102, v98, v94
	v_fma_f32 v103, v101, s2, -v97
	v_add_f32_e32 v101, v101, v102
	v_cvt_pk_bf16_f32 v103, v103, v17
	ds_write_b16 v105, v103 offset:62400
	v_sub_f32_e32 v102, v99, v95
	v_fma_f32 v104, v101, s2, -v98
	v_add_f32_e32 v101, v101, v102
	v_cvt_pk_bf16_f32 v104, v104, v17
	ds_write_b16 v105, v104 offset:63440
	v_sub_f32_e32 v102, v100, v96
	v_fma_f32 v103, v101, s2, -v99
	v_add_f32_e32 v101, v101, v102
	v_cvt_pk_bf16_f32 v103, v103, v17
	ds_write_b16 v105, v103 offset:64480
	v_fma_f32 v104, v101, s2, -v100
	v_cvt_pk_bf16_f32 v104, v104, v17
	ds_write_b16 v105, v104 offset:65520
	v_mov_b32_e32 v1, v104
	s_branch .Lpool_join
.Lpool_w2:
	s_mov_b32 s2, 0x3f000000
	v_add_f32_e32 v101, 0, v36
	v_add_f32_e32 v101, v101, v35
	v_sub_f32_e32 v102, v37, v35
	v_fma_f32 v103, v101, s2, -v36
	v_add_f32_e32 v101, v101, v102
	v_cvt_pk_bf16_f32 v103, v103, v17
	ds_write_b16 v105, v103 offset:0
	v_sub_f32_e32 v102, v38, v36
	v_fma_f32 v104, v101, s2, -v37
	v_add_f32_e32 v101, v101, v102
	v_cvt_pk_bf16_f32 v104, v104, v17
	ds_write_b16 v105, v104 offset:1040
	v_sub_f32_e32 v102, v39, v37
	v_fma_f32 v103, v101, s2, -v38
	v_add_f32_e32 v101, v101, v102
	v_cvt_pk_bf16_f32 v103, v103, v17
	ds_write_b16 v105, v103 offset:2080
	v_sub_f32_e32 v102, v40, v38
	v_fma_f32 v104, v101, s2, -v39
	v_add_f32_e32 v101, v101, v102
	v_cvt_pk_bf16_f32 v104, v104, v17
	ds_write_b16 v105, v104 offset:3120
	v_sub_f32_e32 v102, v41, v39
	v_fma_f32 v103, v101, s2, -v40
	v_add_f32_e32 v101, v101, v102
	v_cvt_pk_bf16_f32 v103, v103, v17
	ds_write_b16 v105, v103 offset:4160
	v_sub_f32_e32 v102, v42, v40
	v_fma_f32 v104, v101, s2, -v41
	v_add_f32_e32 v101, v101, v102
	v_cvt_pk_bf16_f32 v104, v104, v17
	ds_write_b16 v105, v104 offset:5200
	v_sub_f32_e32 v102, v43, v41
	v_fma_f32 v103, v101, s2, -v42
	v_add_f32_e32 v101, v101, v102
	v_cvt_pk_bf16_f32 v103, v103, v17
	ds_write_b16 v105, v103 offset:6240
	v_sub_f32_e32 v102, v44, v42
	v_fma_f32 v104, v101, s2, -v43
	v_add_f32_e32 v101, v101, v102
	v_cvt_pk_bf16_f32 v104, v104, v17
	ds_write_b16 v105, v104 offset:7280
	v_sub_f32_e32 v102, v45, v43
	v_fma_f32 v103, v101, s2, -v44
	v_add_f32_e32 v101, v101, v102
	v_cvt_pk_bf16_f32 v103, v103, v17
	ds_write_b16 v105, v103 offset:8320
	v_sub_f32_e32 v102, v46, v44
	v_fma_f32 v104, v101, s2, -v45
	v_add_f32_e32 v101, v101, v102
	v_cvt_pk_bf16_f32 v104, v104, v17
	ds_write_b16 v105, v104 offset:9360
	v_sub_f32_e32 v102, v47, v45
	v_fma_f32 v103, v101, s2, -v46
	v_add_f32_e32 v101, v101, v102
	v_cvt_pk_bf16_f32 v103, v103, v17
	ds_write_b16 v105, v103 offset:10400
	v_sub_f32_e32 v102, v48, v46
	v_fma_f32 v104, v101, s2, -v47
	v_add_f32_e32 v101, v101, v102
	v_cvt_pk_bf16_f32 v104, v104, v17
	ds_write_b16 v105, v104 offset:11440
	v_sub_f32_e32 v102, v49, v47
	v_fma_f32 v103, v101, s2, -v48
	v_add_f32_e32 v101, v101, v102
	v_cvt_pk_bf16_f32 v103, v103, v17
	ds_write_b16 v105, v103 offset:12480
	v_sub_f32_e32 v102, v50, v48
	v_fma_f32 v104, v101, s2, -v49
	v_add_f32_e32 v101, v101, v102
	v_cvt_pk_bf16_f32 v104, v104, v17
	ds_write_b16 v105, v104 offset:13520
	v_sub_f32_e32 v102, v51, v49
	v_fma_f32 v103, v101, s2, -v50
	v_add_f32_e32 v101, v101, v102
	v_cvt_pk_bf16_f32 v103, v103, v17
	ds_write_b16 v105, v103 offset:14560
	v_sub_f32_e32 v102, v52, v50
	v_fma_f32 v104, v101, s2, -v51
	v_add_f32_e32 v101, v101, v102
	v_cvt_pk_bf16_f32 v104, v104, v17
	ds_write_b16 v105, v104 offset:15600
	v_sub_f32_e32 v102, v53, v51
	v_fma_f32 v103, v101, s2, -v52
	v_add_f32_e32 v101, v101, v102
	v_cvt_pk_bf16_f32 v103, v103, v17
	ds_write_b16 v105, v103 offset:16640
	v_sub_f32_e32 v102, v54, v52
	v_fma_f32 v104, v101, s2, -v53
	v_add_f32_e32 v101, v101, v102
	v_cvt_pk_bf16_f32 v104, v104, v17
	ds_write_b16 v105, v104 offset:17680
	v_sub_f32_e32 v102, v55, v53
	v_fma_f32 v103, v101, s2, -v54
	v_add_f32_e32 v101, v101, v102
	v_cvt_pk_bf16_f32 v103, v103, v17
	ds_write_b16 v105, v103 offset:18720
	v_sub_f32_e32 v102, v56, v54
	v_fma_f32 v104, v101, s2, -v55
	v_add_f32_e32 v101, v101, v102
	v_cvt_pk_bf16_f32 v104, v104, v17
	ds_write_b16 v105, v104 offset:19760
	v_sub_f32_e32 v102, v57, v55
	v_fma_f32 v103, v101, s2, -v56
	v_add_f32_e32 v101, v101, v102
	v_cvt_pk_bf16_f32 v103, v103, v17
	ds_write_b16 v105, v103 offset:20800
	v_sub_f32_e32 v102, v58, v56
	v_fma_f32 v104, v101, s2, -v57
	v_add_f32_e32 v101, v101, v102
	v_cvt_pk_bf16_f32 v104, v104, v17
	ds_write_b16 v105, v104 offset:21840
	v_sub_f32_e32 v102, v59, v57
	v_fma_f32 v103, v101, s2, -v58
	v_add_f32_e32 v101, v101, v102
	v_cvt_pk_bf16_f32 v103, v103, v17
	ds_write_b16 v105, v103 offset:22880
	v_sub_f32_e32 v102, v60, v58
	v_fma_f32 v104, v101, s2, -v59
	v_add_f32_e32 v101, v101, v102
	v_cvt_pk_bf16_f32 v104, v104, v17
	ds_write_b16 v105, v104 offset:23920
	v_sub_f32_e32 v102, v61, v59
	v_fma_f32 v103, v101, s2, -v60
	v_add_f32_e32 v101, v101, v102
	v_cvt_pk_bf16_f32 v103, v103, v17
	ds_write_b16 v105, v103 offset:24960
	v_sub_f32_e32 v102, v62, v60
	v_fma_f32 v104, v101, s2, -v61
	v_add_f32_e32 v101, v101, v102
	v_cvt_pk_bf16_f32 v104, v104, v17
	ds_write_b16 v105, v104 offset:26000
	v_sub_f32_e32 v102, v63, v61
	v_fma_f32 v103, v101, s2, -v62
	v_add_f32_e32 v101, v101, v102
	v_cvt_pk_bf16_f32 v103, v103, v17
	ds_write_b16 v105, v103 offset:27040
	v_sub_f32_e32 v102, v64, v62
	v_fma_f32 v104, v101, s2, -v63
	v_add_f32_e32 v101, v101, v102
	v_cvt_pk_bf16_f32 v104, v104, v17
	ds_write_b16 v105, v104 offset:28080
	v_sub_f32_e32 v102, v65, v63
	v_fma_f32 v103, v101, s2, -v64
	v_add_f32_e32 v101, v101, v102
	v_cvt_pk_bf16_f32 v103, v103, v17
	ds_write_b16 v105, v103 offset:29120
	v_sub_f32_e32 v102, v66, v64
	v_fma_f32 v104, v101, s2, -v65
	v_add_f32_e32 v101, v101, v102
	v_cvt_pk_bf16_f32 v104, v104, v17
	ds_write_b16 v105, v104 offset:30160
	v_sub_f32_e32 v102, v67, v65
	v_fma_f32 v103, v101, s2, -v66
	v_add_f32_e32 v101, v101, v102
	v_cvt_pk_bf16_f32 v103, v103, v17
	ds_write_b16 v105, v103 offset:31200
	v_sub_f32_e32 v102, v68, v66
	v_fma_f32 v104, v101, s2, -v67
	v_add_f32_e32 v101, v101, v102
	v_cvt_pk_bf16_f32 v104, v104, v17
	ds_write_b16 v105, v104 offset:32240
	v_sub_f32_e32 v102, v69, v67
	v_fma_f32 v103, v101, s2, -v68
	v_add_f32_e32 v101, v101, v102
	v_cvt_pk_bf16_f32 v103, v103, v17
	ds_write_b16 v105, v103 offset:33280
	v_sub_f32_e32 v102, v70, v68
	v_fma_f32 v104, v101, s2, -v69
	v_add_f32_e32 v101, v101, v102
	v_cvt_pk_bf16_f32 v104, v104, v17
	ds_write_b16 v105, v104 offset:34320
	v_sub_f32_e32 v102, v71, v69
	v_fma_f32 v103, v101, s2, -v70
	v_add_f32_e32 v101, v101, v102
	v_cvt_pk_bf16_f32 v103, v103, v17
	ds_write_b16 v105, v103 offset:35360
	v_sub_f32_e32 v102, v72, v70
	v_fma_f32 v104, v101, s2, -v71
	v_add_f32_e32 v101, v101, v102
	v_cvt_pk_bf16_f32 v104, v104, v17
	ds_write_b16 v105, v104 offset:36400
	v_sub_f32_e32 v102, v73, v71
	v_fma_f32 v103, v101, s2, -v72
	v_add_f32_e32 v101, v101, v102
	v_cvt_pk_bf16_f32 v103, v103, v17
	ds_write_b16 v105, v103 offset:37440
	v_sub_f32_e32 v102, v74, v72
	v_fma_f32 v104, v101, s2, -v73
	v_add_f32_e32 v101, v101, v102
	v_cvt_pk_bf16_f32 v104, v104, v17
	ds_write_b16 v105, v104 offset:38480
	v_sub_f32_e32 v102, v75, v73
	v_fma_f32 v103, v101, s2, -v74
	v_add_f32_e32 v101, v101, v102
	v_cvt_pk_bf16_f32 v103, v103, v17
	ds_write_b16 v105, v103 offset:39520
	v_sub_f32_e32 v102, v76, v74
	v_fma_f32 v104, v101, s2, -v75
	v_add_f32_e32 v101, v101, v102
	v_cvt_pk_bf16_f32 v104, v104, v17
	ds_write_b16 v105, v104 offset:40560
	v_sub_f32_e32 v102, v77, v75
	v_fma_f32 v103, v101, s2, -v76
	v_add_f32_e32 v101, v101, v102
	v_cvt_pk_bf16_f32 v103, v103, v17
	ds_write_b16 v105, v103 offset:41600
	v_sub_f32_e32 v102, v79, v76
	v_fma_f32 v104, v101, s2, -v77
	v_add_f32_e32 v101, v101, v102
	v_cvt_pk_bf16_f32 v104, v104, v17
	ds_write_b16 v105, v104 offset:42640
	v_sub_f32_e32 v102, v80, v77
	v_fma_f32 v103, v101, s2, -v79
	v_add_f32_e32 v101, v101, v102
	v_cvt_pk_bf16_f32 v103, v103, v17
	ds_write_b16 v105, v103 offset:43680
	v_sub_f32_e32 v102, v81, v79
	v_fma_f32 v104, v101, s2, -v80
	v_add_f32_e32 v101, v101, v102
	v_cvt_pk_bf16_f32 v104, v104, v17
	ds_write_b16 v105, v104 offset:44720
	v_sub_f32_e32 v102, v82, v80
	v_fma_f32 v103, v101, s2, -v81
	v_add_f32_e32 v101, v101, v102
	v_cvt_pk_bf16_f32 v103, v103, v17
	ds_write_b16 v105, v103 offset:45760
	v_sub_f32_e32 v102, v83, v81
	v_fma_f32 v104, v101, s2, -v82
	v_add_f32_e32 v101, v101, v102
	v_cvt_pk_bf16_f32 v104, v104, v17
	ds_write_b16 v105, v104 offset:46800
	v_sub_f32_e32 v102, v84, v82
	v_fma_f32 v103, v101, s2, -v83
	v_add_f32_e32 v101, v101, v102
	v_cvt_pk_bf16_f32 v103, v103, v17
	ds_write_b16 v105, v103 offset:47840
	v_sub_f32_e32 v102, v85, v83
	v_fma_f32 v104, v101, s2, -v84
	v_add_f32_e32 v101, v101, v102
	v_cvt_pk_bf16_f32 v104, v104, v17
	ds_write_b16 v105, v104 offset:48880
	v_sub_f32_e32 v102, v86, v84
	v_fma_f32 v103, v101, s2, -v85
	v_add_f32_e32 v101, v101, v102
	v_cvt_pk_bf16_f32 v103, v103, v17
	ds_write_b16 v105, v103 offset:49920
	v_sub_f32_e32 v102, v87, v85
	v_fma_f32 v104, v101, s2, -v86
	v_add_f32_e32 v101, v101, v102
	v_cvt_pk_bf16_f32 v104, v104, v17
	ds_write_b16 v105, v104 offset:50960
	v_sub_f32_e32 v102, v88, v86
	v_fma_f32 v103, v101, s2, -v87
	v_add_f32_e32 v101, v101, v102
	v_cvt_pk_bf16_f32 v103, v103, v17
	ds_write_b16 v105, v103 offset:52000
	v_sub_f32_e32 v102, v89, v87
	v_fma_f32 v104, v101, s2, -v88
	v_add_f32_e32 v101, v101, v102
	v_cvt_pk_bf16_f32 v104, v104, v17
	ds_write_b16 v105, v104 offset:53040
	v_sub_f32_e32 v102, v90, v88
	v_fma_f32 v103, v101, s2, -v89
	v_add_f32_e32 v101, v101, v102
	v_cvt_pk_bf16_f32 v103, v103, v17
	ds_write_b16 v105, v103 offset:54080
	v_sub_f32_e32 v102, v91, v89
	v_fma_f32 v104, v101, s2, -v90
	v_add_f32_e32 v101, v101, v102
	v_cvt_pk_bf16_f32 v104, v104, v17
	ds_write_b16 v105, v104 offset:55120
	v_sub_f32_e32 v102, v92, v90
	v_fma_f32 v103, v101, s2, -v91
	v_add_f32_e32 v101, v101, v102
	v_cvt_pk_bf16_f32 v103, v103, v17
	ds_write_b16 v105, v103 offset:56160
	v_sub_f32_e32 v102, v93, v91
	v_fma_f32 v104, v101, s2, -v92
	v_add_f32_e32 v101, v101, v102
	v_cvt_pk_bf16_f32 v104, v104, v17
	ds_write_b16 v105, v104 offset:57200
	v_sub_f32_e32 v102, v94, v92
	v_fma_f32 v103, v101, s2, -v93
	v_add_f32_e32 v101, v101, v102
	v_cvt_pk_bf16_f32 v103, v103, v17
	ds_write_b16 v105, v103 offset:58240
	v_sub_f32_e32 v102, v95, v93
	v_fma_f32 v104, v101, s2, -v94
	v_add_f32_e32 v101, v101, v102
	v_cvt_pk_bf16_f32 v104, v104, v17
	ds_write_b16 v105, v104 offset:59280
	v_sub_f32_e32 v102, v96, v94
	v_fma_f32 v103, v101, s2, -v95
	v_add_f32_e32 v101, v101, v102
	v_cvt_pk_bf16_f32 v103, v103, v17
	ds_write_b16 v105, v103 offset:60320
	v_sub_f32_e32 v102, v97, v95
	v_fma_f32 v104, v101, s2, -v96
	v_add_f32_e32 v101, v101, v102
	v_cvt_pk_bf16_f32 v104, v104, v17
	ds_write_b16 v105, v104 offset:61360
	v_sub_f32_e32 v102, v98, v96
	v_fma_f32 v103, v101, s2, -v97
	v_add_f32_e32 v101, v101, v102
	v_cvt_pk_bf16_f32 v103, v103, v17
	ds_write_b16 v105, v103 offset:62400
	v_sub_f32_e32 v102, v99, v97
	v_fma_f32 v104, v101, s2, -v98
	v_add_f32_e32 v101, v101, v102
	v_cvt_pk_bf16_f32 v104, v104, v17
	ds_write_b16 v105, v104 offset:63440
	v_sub_f32_e32 v102, v100, v98
	v_fma_f32 v103, v101, s2, -v99
	v_add_f32_e32 v101, v101, v102
	v_cvt_pk_bf16_f32 v103, v103, v17
	ds_write_b16 v105, v103 offset:64480
	v_fma_f32 v104, v101, s2, -v100
	v_cvt_pk_bf16_f32 v104, v104, v17
	ds_write_b16 v105, v104 offset:65520
	v_mov_b32_e32 v1, v104
	s_branch .Lpool_join
.Lpool_join:
	v_mov_b32_e32 v0, v228
	s_mov_b64 s[4:5], exec
	s_branch .LBB0_674
